# code placement (asm guide 9.3): all nine GEMM K-loop heads aligned to 64 B with .p2align 6 (s_nop padding), on top of v69
# speedup vs baseline: 1.0019x; 1.0019x over previous
.LBB0_223:
	s_ashr_i32 s71, s70, 31
	s_lshl_b64 s[26:27], s[70:71], 21
	s_add_u32 s74, s31, s26
	s_addc_u32 s75, s34, s27
	s_and_b64 s[26:27], s[72:73], exec
	s_cselect_b32 s28, s75, s3
	s_cselect_b32 s29, s74, s2
	s_ashr_i32 s69, s68, 31
	s_lshl_b64 s[26:27], s[68:69], 21
	s_add_u32 s76, s35, s26
	s_addc_u32 s77, s52, s27
	s_and_b64 s[26:27], s[72:73], exec
	s_cselect_b32 s33, s77, s25
	s_cselect_b32 s69, s76, s24
	s_add_u32 s2, s2, 0x100080
	s_addc_u32 s3, s3, 0
	s_add_u32 s71, s24, 0x100
	v_mov_b32_e32 v2, 0
	s_mov_b32 s93, s87
	s_addc_u32 s81, s25, 0
	s_mov_b32 s82, -2
	s_waitcnt lgkmcnt(0)
	v_mov_b32_e32 v3, v2
	v_mov_b32_e32 v4, v2
	v_mov_b32_e32 v5, v2
	v_mov_b32_e32 v14, v2
	v_mov_b32_e32 v15, v2
	v_mov_b32_e32 v16, v2
	v_mov_b32_e32 v17, v2
	v_mov_b32_e32 v18, v2
	v_mov_b32_e32 v19, v2
	v_mov_b32_e32 v20, v2
	v_mov_b32_e32 v21, v2
	v_mov_b32_e32 v30, v2
	v_mov_b32_e32 v31, v2
	v_mov_b32_e32 v32, v2
	v_mov_b32_e32 v33, v2
	v_mov_b32_e32 v34, v2
	v_mov_b32_e32 v35, v2
	v_mov_b32_e32 v36, v2
	v_mov_b32_e32 v37, v2
	v_mov_b32_e32 v46, v2
	v_mov_b32_e32 v47, v2
	v_mov_b32_e32 v48, v2
	v_mov_b32_e32 v49, v2
	v_mov_b32_e32 v50, v2
	v_mov_b32_e32 v51, v2
	v_mov_b32_e32 v52, v2
	v_mov_b32_e32 v53, v2
	v_mov_b32_e32 v62, v2
	v_mov_b32_e32 v63, v2
	v_mov_b32_e32 v64, v2
	v_mov_b32_e32 v65, v2
	v_mov_b32_e32 v6, v2
	v_mov_b32_e32 v7, v2
	v_mov_b32_e32 v8, v2
	v_mov_b32_e32 v9, v2
	v_mov_b32_e32 v10, v2
	v_mov_b32_e32 v11, v2
	v_mov_b32_e32 v12, v2
	v_mov_b32_e32 v13, v2
	v_mov_b32_e32 v22, v2
	v_mov_b32_e32 v23, v2
	v_mov_b32_e32 v24, v2
	v_mov_b32_e32 v25, v2
	v_mov_b32_e32 v26, v2
	v_mov_b32_e32 v27, v2
	v_mov_b32_e32 v28, v2
	v_mov_b32_e32 v29, v2
	v_mov_b32_e32 v38, v2
	v_mov_b32_e32 v39, v2
	v_mov_b32_e32 v40, v2
	v_mov_b32_e32 v41, v2
	v_mov_b32_e32 v42, v2
	v_mov_b32_e32 v43, v2
	v_mov_b32_e32 v44, v2
	v_mov_b32_e32 v45, v2
	v_mov_b32_e32 v54, v2
	v_mov_b32_e32 v55, v2
	v_mov_b32_e32 v56, v2
	v_mov_b32_e32 v57, v2
	v_mov_b32_e32 v58, v2
	v_mov_b32_e32 v59, v2
	v_mov_b32_e32 v60, v2
	v_mov_b32_e32 v61, v2
	v_mov_b32_e32 v66, v2
	v_mov_b32_e32 v67, v2
	v_mov_b32_e32 v68, v2
	v_mov_b32_e32 v69, v2
	v_mov_b32_e32 v78, v2
	v_mov_b32_e32 v79, v2
	v_mov_b32_e32 v80, v2
	v_mov_b32_e32 v81, v2
	v_mov_b32_e32 v82, v2
	v_mov_b32_e32 v83, v2
	v_mov_b32_e32 v84, v2
	v_mov_b32_e32 v85, v2
	v_mov_b32_e32 v94, v2
	v_mov_b32_e32 v95, v2
	v_mov_b32_e32 v96, v2
	v_mov_b32_e32 v97, v2
	v_mov_b32_e32 v98, v2
	v_mov_b32_e32 v99, v2
	v_mov_b32_e32 v100, v2
	v_mov_b32_e32 v101, v2
	v_mov_b32_e32 v110, v2
	v_mov_b32_e32 v111, v2
	v_mov_b32_e32 v112, v2
	v_mov_b32_e32 v113, v2
	v_mov_b32_e32 v118, v2
	v_mov_b32_e32 v119, v2
	v_mov_b32_e32 v120, v2
	v_mov_b32_e32 v121, v2
	v_mov_b32_e32 v126, v2
	v_mov_b32_e32 v127, v2
	v_mov_b32_e32 v128, v2
	v_mov_b32_e32 v129, v2
	v_mov_b32_e32 v70, v2
	v_mov_b32_e32 v71, v2
	v_mov_b32_e32 v72, v2
	v_mov_b32_e32 v73, v2
	v_mov_b32_e32 v74, v2
	v_mov_b32_e32 v75, v2
	v_mov_b32_e32 v76, v2
	v_mov_b32_e32 v77, v2
	v_mov_b32_e32 v86, v2
	v_mov_b32_e32 v87, v2
	v_mov_b32_e32 v88, v2
	v_mov_b32_e32 v89, v2
	v_mov_b32_e32 v90, v2
	v_mov_b32_e32 v91, v2
	v_mov_b32_e32 v92, v2
	v_mov_b32_e32 v93, v2
	v_mov_b32_e32 v102, v2
	v_mov_b32_e32 v103, v2
	v_mov_b32_e32 v104, v2
	v_mov_b32_e32 v105, v2
	v_mov_b32_e32 v106, v2
	v_mov_b32_e32 v107, v2
	v_mov_b32_e32 v108, v2
	v_mov_b32_e32 v109, v2
	v_mov_b32_e32 v114, v2
	v_mov_b32_e32 v115, v2
	v_mov_b32_e32 v116, v2
	v_mov_b32_e32 v117, v2
	v_mov_b32_e32 v122, v2
	v_mov_b32_e32 v123, v2
	v_mov_b32_e32 v124, v2
	v_mov_b32_e32 v125, v2
	.p2align	6

.LBB0_475:
	s_ashr_i32 s15, s14, 31
	s_lshl_b64 s[26:27], s[14:15], 21
	s_add_u32 s40, s31, s26
	s_addc_u32 s41, s34, s27
	s_and_b64 s[26:27], s[38:39], exec
	s_cselect_b32 s15, s41, s25
	s_cselect_b32 s28, s40, s24
	s_ashr_i32 s13, s12, 31
	s_lshl_b64 s[26:27], s[12:13], 21
	s_add_u32 s42, s35, s26
	s_addc_u32 s43, s44, s27
	s_and_b64 s[26:27], s[38:39], exec
	s_cselect_b32 s13, s43, s3
	s_cselect_b32 s29, s42, s2
	s_add_u32 s24, s24, 0x100080
	s_addc_u32 s25, s25, 0
	s_add_u32 s33, s2, 0x100
	v_mov_b32_e32 v10, 0
	s_addc_u32 s61, s3, 0
	s_mov_b32 s62, -2
	v_mov_b32_e32 v11, v10
	v_mov_b32_e32 v12, v10
	v_mov_b32_e32 v13, v10
	v_mov_b32_e32 v14, v10
	v_mov_b32_e32 v15, v10
	v_mov_b32_e32 v16, v10
	v_mov_b32_e32 v17, v10
	v_mov_b32_e32 v26, v10
	v_mov_b32_e32 v27, v10
	v_mov_b32_e32 v28, v10
	v_mov_b32_e32 v29, v10
	v_mov_b32_e32 v30, v10
	v_mov_b32_e32 v31, v10
	v_mov_b32_e32 v32, v10
	v_mov_b32_e32 v33, v10
	v_mov_b32_e32 v42, v10
	v_mov_b32_e32 v43, v10
	v_mov_b32_e32 v44, v10
	v_mov_b32_e32 v45, v10
	v_mov_b32_e32 v46, v10
	v_mov_b32_e32 v47, v10
	v_mov_b32_e32 v48, v10
	v_mov_b32_e32 v49, v10
	v_mov_b32_e32 v58, v10
	v_mov_b32_e32 v59, v10
	v_mov_b32_e32 v60, v10
	v_mov_b32_e32 v61, v10
	v_mov_b32_e32 v62, v10
	v_mov_b32_e32 v63, v10
	v_mov_b32_e32 v64, v10
	v_mov_b32_e32 v65, v10
	v_mov_b32_e32 v2, v10
	v_mov_b32_e32 v3, v10
	v_mov_b32_e32 v4, v10
	v_mov_b32_e32 v5, v10
	v_mov_b32_e32 v6, v10
	v_mov_b32_e32 v7, v10
	v_mov_b32_e32 v8, v10
	v_mov_b32_e32 v9, v10
	v_mov_b32_e32 v18, v10
	v_mov_b32_e32 v19, v10
	v_mov_b32_e32 v20, v10
	v_mov_b32_e32 v21, v10
	v_mov_b32_e32 v22, v10
	v_mov_b32_e32 v23, v10
	v_mov_b32_e32 v24, v10
	v_mov_b32_e32 v25, v10
	v_mov_b32_e32 v34, v10
	v_mov_b32_e32 v35, v10
	v_mov_b32_e32 v36, v10
	v_mov_b32_e32 v37, v10
	v_mov_b32_e32 v38, v10
	v_mov_b32_e32 v39, v10
	v_mov_b32_e32 v40, v10
	v_mov_b32_e32 v41, v10
	v_mov_b32_e32 v50, v10
	v_mov_b32_e32 v51, v10
	v_mov_b32_e32 v52, v10
	v_mov_b32_e32 v53, v10
	v_mov_b32_e32 v54, v10
	v_mov_b32_e32 v55, v10
	v_mov_b32_e32 v56, v10
	v_mov_b32_e32 v57, v10
	v_mov_b32_e32 v74, v10
	v_mov_b32_e32 v75, v10
	v_mov_b32_e32 v76, v10
	v_mov_b32_e32 v77, v10
	v_mov_b32_e32 v78, v10
	v_mov_b32_e32 v79, v10
	v_mov_b32_e32 v80, v10
	v_mov_b32_e32 v81, v10
	v_mov_b32_e32 v90, v10
	v_mov_b32_e32 v91, v10
	v_mov_b32_e32 v92, v10
	v_mov_b32_e32 v93, v10
	v_mov_b32_e32 v94, v10
	v_mov_b32_e32 v95, v10
	v_mov_b32_e32 v96, v10
	v_mov_b32_e32 v97, v10
	v_mov_b32_e32 v106, v10
	v_mov_b32_e32 v107, v10
	v_mov_b32_e32 v108, v10
	v_mov_b32_e32 v109, v10
	v_mov_b32_e32 v110, v10
	v_mov_b32_e32 v111, v10
	v_mov_b32_e32 v112, v10
	v_mov_b32_e32 v113, v10
	v_mov_b32_e32 v122, v10
	v_mov_b32_e32 v123, v10
	v_mov_b32_e32 v124, v10
	v_mov_b32_e32 v125, v10
	v_mov_b32_e32 v126, v10
	v_mov_b32_e32 v127, v10
	v_mov_b32_e32 v128, v10
	v_mov_b32_e32 v129, v10
	v_mov_b32_e32 v66, v10
	v_mov_b32_e32 v67, v10
	v_mov_b32_e32 v68, v10
	v_mov_b32_e32 v69, v10
	v_mov_b32_e32 v70, v10
	v_mov_b32_e32 v71, v10
	v_mov_b32_e32 v72, v10
	v_mov_b32_e32 v73, v10
	v_mov_b32_e32 v82, v10
	v_mov_b32_e32 v83, v10
	v_mov_b32_e32 v84, v10
	v_mov_b32_e32 v85, v10
	v_mov_b32_e32 v86, v10
	v_mov_b32_e32 v87, v10
	v_mov_b32_e32 v88, v10
	v_mov_b32_e32 v89, v10
	v_mov_b32_e32 v98, v10
	v_mov_b32_e32 v99, v10
	v_mov_b32_e32 v100, v10
	v_mov_b32_e32 v101, v10
	v_mov_b32_e32 v102, v10
	v_mov_b32_e32 v103, v10
	v_mov_b32_e32 v104, v10
	v_mov_b32_e32 v105, v10
	v_mov_b32_e32 v114, v10
	v_mov_b32_e32 v115, v10
	v_mov_b32_e32 v116, v10
	v_mov_b32_e32 v117, v10
	v_mov_b32_e32 v118, v10
	v_mov_b32_e32 v119, v10
	v_mov_b32_e32 v120, v10
	v_mov_b32_e32 v121, v10
	.p2align	6

.LBB0_716:
	s_add_u32 s2, s2, 0x2b0080
	s_addc_u32 s3, s3, 0
	s_add_u32 s56, s24, 0x100
	v_mov_b32_e32 v2, 0
	s_addc_u32 s57, s25, 0
	s_mov_b32 s58, -2
	s_waitcnt lgkmcnt(0)
	v_mov_b32_e32 v3, v2
	v_mov_b32_e32 v4, v2
	v_mov_b32_e32 v5, v2
	v_mov_b32_e32 v6, v2
	v_mov_b32_e32 v7, v2
	v_mov_b32_e32 v8, v2
	v_mov_b32_e32 v9, v2
	v_mov_b32_e32 v18, v2
	v_mov_b32_e32 v19, v2
	v_mov_b32_e32 v20, v2
	v_mov_b32_e32 v21, v2
	v_mov_b32_e32 v22, v2
	v_mov_b32_e32 v23, v2
	v_mov_b32_e32 v24, v2
	v_mov_b32_e32 v25, v2
	v_mov_b32_e32 v34, v2
	v_mov_b32_e32 v35, v2
	v_mov_b32_e32 v36, v2
	v_mov_b32_e32 v37, v2
	v_mov_b32_e32 v38, v2
	v_mov_b32_e32 v39, v2
	v_mov_b32_e32 v40, v2
	v_mov_b32_e32 v41, v2
	v_mov_b32_e32 v50, v2
	v_mov_b32_e32 v51, v2
	v_mov_b32_e32 v52, v2
	v_mov_b32_e32 v53, v2
	v_mov_b32_e32 v54, v2
	v_mov_b32_e32 v55, v2
	v_mov_b32_e32 v56, v2
	v_mov_b32_e32 v57, v2
	v_mov_b32_e32 v10, v2
	v_mov_b32_e32 v11, v2
	v_mov_b32_e32 v12, v2
	v_mov_b32_e32 v13, v2
	v_mov_b32_e32 v14, v2
	v_mov_b32_e32 v15, v2
	v_mov_b32_e32 v16, v2
	v_mov_b32_e32 v17, v2
	v_mov_b32_e32 v26, v2
	v_mov_b32_e32 v27, v2
	v_mov_b32_e32 v28, v2
	v_mov_b32_e32 v29, v2
	v_mov_b32_e32 v30, v2
	v_mov_b32_e32 v31, v2
	v_mov_b32_e32 v32, v2
	v_mov_b32_e32 v33, v2
	v_mov_b32_e32 v42, v2
	v_mov_b32_e32 v43, v2
	v_mov_b32_e32 v44, v2
	v_mov_b32_e32 v45, v2
	v_mov_b32_e32 v46, v2
	v_mov_b32_e32 v47, v2
	v_mov_b32_e32 v48, v2
	v_mov_b32_e32 v49, v2
	v_mov_b32_e32 v58, v2
	v_mov_b32_e32 v59, v2
	v_mov_b32_e32 v60, v2
	v_mov_b32_e32 v61, v2
	v_mov_b32_e32 v62, v2
	v_mov_b32_e32 v63, v2
	v_mov_b32_e32 v64, v2
	v_mov_b32_e32 v65, v2
	v_mov_b32_e32 v66, v2
	v_mov_b32_e32 v67, v2
	v_mov_b32_e32 v68, v2
	v_mov_b32_e32 v69, v2
	v_mov_b32_e32 v70, v2
	v_mov_b32_e32 v71, v2
	v_mov_b32_e32 v72, v2
	v_mov_b32_e32 v73, v2
	v_mov_b32_e32 v82, v2
	v_mov_b32_e32 v83, v2
	v_mov_b32_e32 v84, v2
	v_mov_b32_e32 v85, v2
	v_mov_b32_e32 v86, v2
	v_mov_b32_e32 v87, v2
	v_mov_b32_e32 v88, v2
	v_mov_b32_e32 v89, v2
	v_mov_b32_e32 v98, v2
	v_mov_b32_e32 v99, v2
	v_mov_b32_e32 v100, v2
	v_mov_b32_e32 v101, v2
	v_mov_b32_e32 v102, v2
	v_mov_b32_e32 v103, v2
	v_mov_b32_e32 v104, v2
	v_mov_b32_e32 v105, v2
	v_mov_b32_e32 v114, v2
	v_mov_b32_e32 v115, v2
	v_mov_b32_e32 v116, v2
	v_mov_b32_e32 v117, v2
	v_mov_b32_e32 v118, v2
	v_mov_b32_e32 v119, v2
	v_mov_b32_e32 v120, v2
	v_mov_b32_e32 v121, v2
	v_mov_b32_e32 v74, v2
	v_mov_b32_e32 v75, v2
	v_mov_b32_e32 v76, v2
	v_mov_b32_e32 v77, v2
	v_mov_b32_e32 v78, v2
	v_mov_b32_e32 v79, v2
	v_mov_b32_e32 v80, v2
	v_mov_b32_e32 v81, v2
	v_mov_b32_e32 v90, v2
	v_mov_b32_e32 v91, v2
	v_mov_b32_e32 v92, v2
	v_mov_b32_e32 v93, v2
	v_mov_b32_e32 v94, v2
	v_mov_b32_e32 v95, v2
	v_mov_b32_e32 v96, v2
	v_mov_b32_e32 v97, v2
	v_mov_b32_e32 v106, v2
	v_mov_b32_e32 v107, v2
	v_mov_b32_e32 v108, v2
	v_mov_b32_e32 v109, v2
	v_mov_b32_e32 v110, v2
	v_mov_b32_e32 v111, v2
	v_mov_b32_e32 v112, v2
	v_mov_b32_e32 v113, v2
	v_mov_b32_e32 v122, v2
	v_mov_b32_e32 v123, v2
	v_mov_b32_e32 v124, v2
	v_mov_b32_e32 v125, v2
	v_mov_b32_e32 v126, v2
	v_mov_b32_e32 v127, v2
	v_mov_b32_e32 v128, v2
	v_mov_b32_e32 v129, v2
	.p2align	6

.LBB0_742:
	s_lshr_b32 s33, s87, 3
	s_cmp_eq_u32 s0, 3
	s_cselect_b32 s24, 44, 46
	s_and_b64 s[14:15], s[14:15], exec
	v_lshlrev_b32_e32 v11, 2, v155
	s_cselect_b32 s35, 36, s24
	v_lshl_or_b32 v10, v155, 6, v184
	v_and_b32_e32 v11, 32, v11
	s_lshl_b32 s14, s23, 5
	s_lshl_b32 s15, s22, 13
	s_and_b32 s28, s14, 0x60
	v_bitop3_b32 v10, v10, s15, v11 bitop3:0xde
	s_mov_b64 s[14:15], 0x80
	s_add_i32 m0, s29, 0x18000
	v_lshl_add_u64 v[2:3], v[2:3], 0, s[14:15]
	s_waitcnt vmcnt(2)
	s_barrier
	global_load_lds_dwordx4 v[2:3], off
	v_lshl_add_u64 v[2:3], v[4:5], 0, s[14:15]
	s_add_i32 m0, s29, 0x1a000
	s_add_i32 s36, s29, 0x8000
	s_add_i32 s37, s29, 0xa000
	v_lshl_or_b32 v132, s22, 6, v155
	global_load_lds_dwordx4 v[2:3], off
	v_lshl_add_u64 v[2:3], v[8:9], 0, s[14:15]
	s_mov_b32 m0, s36
	s_add_u32 s22, s2, 0x2b0080
	global_load_lds_dwordx4 v[2:3], off
	v_lshl_add_u64 v[2:3], v[6:7], 0, s[14:15]
	s_mov_b32 m0, s37
	s_addc_u32 s23, s3, 0
	global_load_lds_dwordx4 v[2:3], off
	s_add_i32 m0, s29, 0x1c000
	v_lshl_add_u64 v[2:3], s[22:23], 0, v[158:159]
	global_load_lds_dwordx4 v[2:3], off
	v_lshl_add_u64 v[2:3], s[22:23], 0, v[160:161]
	s_add_i32 m0, s29, 0x1e000
	v_lshl_or_b32 v12, s28, 7, v157
	global_load_lds_dwordx4 v[2:3], off
	s_waitcnt vmcnt(6)
	s_add_i32 s41, 0, 0x10000
	s_add_i32 s43, 0, 0x14000
	s_add_i32 s45, 0, 0x18000
	s_add_i32 s47, 0, 0x1c000
	v_mov_b32_e32 v2, 0
	v_add_u32_e32 v130, s41, v12
	v_add_u32_e32 v131, s43, v12
	s_add_i32 s41, s41, s12
	s_add_i32 s43, s43, s12
	v_add_u32_e32 v134, s45, v12
	v_add_u32_e32 v135, s47, v12
	s_add_i32 s45, s45, s12
	s_add_i32 s47, s47, s12
	s_add_i32 s38, s35, -2
	v_add_u32_e32 v133, 0, v10
	s_add_i32 s39, s29, 0xc000
	s_add_i32 s40, s29, 0xe000
	s_add_i32 s42, s41, 0x2000
	s_add_i32 s44, s43, 0x2000
	s_add_i32 s46, s45, 0x2000
	s_add_i32 s48, s47, 0x2000
	s_mov_b32 s22, 0
	v_mov_b32_e32 v3, v2
	v_mov_b32_e32 v4, v2
	v_mov_b32_e32 v5, v2
	v_mov_b32_e32 v6, v2
	v_mov_b32_e32 v7, v2
	v_mov_b32_e32 v8, v2
	v_mov_b32_e32 v9, v2
	v_mov_b32_e32 v18, v2
	v_mov_b32_e32 v19, v2
	v_mov_b32_e32 v20, v2
	v_mov_b32_e32 v21, v2
	v_mov_b32_e32 v22, v2
	v_mov_b32_e32 v23, v2
	v_mov_b32_e32 v24, v2
	v_mov_b32_e32 v25, v2
	v_mov_b32_e32 v34, v2
	v_mov_b32_e32 v35, v2
	v_mov_b32_e32 v36, v2
	v_mov_b32_e32 v37, v2
	v_mov_b32_e32 v38, v2
	v_mov_b32_e32 v39, v2
	v_mov_b32_e32 v40, v2
	v_mov_b32_e32 v41, v2
	v_mov_b32_e32 v50, v2
	v_mov_b32_e32 v51, v2
	v_mov_b32_e32 v52, v2
	v_mov_b32_e32 v53, v2
	v_mov_b32_e32 v54, v2
	v_mov_b32_e32 v55, v2
	v_mov_b32_e32 v56, v2
	v_mov_b32_e32 v57, v2
	v_mov_b32_e32 v10, v2
	v_mov_b32_e32 v11, v2
	v_mov_b32_e32 v12, v2
	v_mov_b32_e32 v13, v2
	v_mov_b32_e32 v14, v2
	v_mov_b32_e32 v15, v2
	v_mov_b32_e32 v16, v2
	v_mov_b32_e32 v17, v2
	v_mov_b32_e32 v26, v2
	v_mov_b32_e32 v27, v2
	v_mov_b32_e32 v28, v2
	v_mov_b32_e32 v29, v2
	v_mov_b32_e32 v30, v2
	v_mov_b32_e32 v31, v2
	v_mov_b32_e32 v32, v2
	v_mov_b32_e32 v33, v2
	v_mov_b32_e32 v42, v2
	v_mov_b32_e32 v43, v2
	v_mov_b32_e32 v44, v2
	v_mov_b32_e32 v45, v2
	v_mov_b32_e32 v46, v2
	v_mov_b32_e32 v47, v2
	v_mov_b32_e32 v48, v2
	v_mov_b32_e32 v49, v2
	v_mov_b32_e32 v58, v2
	v_mov_b32_e32 v59, v2
	v_mov_b32_e32 v60, v2
	v_mov_b32_e32 v61, v2
	v_mov_b32_e32 v62, v2
	v_mov_b32_e32 v63, v2
	v_mov_b32_e32 v64, v2
	v_mov_b32_e32 v65, v2
	v_mov_b32_e32 v66, v2
	v_mov_b32_e32 v67, v2
	v_mov_b32_e32 v68, v2
	v_mov_b32_e32 v69, v2
	v_mov_b32_e32 v70, v2
	v_mov_b32_e32 v71, v2
	v_mov_b32_e32 v72, v2
	v_mov_b32_e32 v73, v2
	v_mov_b32_e32 v82, v2
	v_mov_b32_e32 v83, v2
	v_mov_b32_e32 v84, v2
	v_mov_b32_e32 v85, v2
	v_mov_b32_e32 v86, v2
	v_mov_b32_e32 v87, v2
	v_mov_b32_e32 v88, v2
	v_mov_b32_e32 v89, v2
	v_mov_b32_e32 v98, v2
	v_mov_b32_e32 v99, v2
	v_mov_b32_e32 v100, v2
	v_mov_b32_e32 v101, v2
	v_mov_b32_e32 v102, v2
	v_mov_b32_e32 v103, v2
	v_mov_b32_e32 v104, v2
	v_mov_b32_e32 v105, v2
	v_mov_b32_e32 v114, v2
	v_mov_b32_e32 v115, v2
	v_mov_b32_e32 v116, v2
	v_mov_b32_e32 v117, v2
	v_mov_b32_e32 v118, v2
	v_mov_b32_e32 v119, v2
	v_mov_b32_e32 v120, v2
	v_mov_b32_e32 v121, v2
	v_mov_b32_e32 v74, v2
	v_mov_b32_e32 v75, v2
	v_mov_b32_e32 v76, v2
	v_mov_b32_e32 v77, v2
	v_mov_b32_e32 v78, v2
	v_mov_b32_e32 v79, v2
	v_mov_b32_e32 v80, v2
	v_mov_b32_e32 v81, v2
	v_mov_b32_e32 v90, v2
	v_mov_b32_e32 v91, v2
	v_mov_b32_e32 v92, v2
	v_mov_b32_e32 v93, v2
	v_mov_b32_e32 v94, v2
	v_mov_b32_e32 v95, v2
	v_mov_b32_e32 v96, v2
	v_mov_b32_e32 v97, v2
	v_mov_b32_e32 v106, v2
	v_mov_b32_e32 v107, v2
	v_mov_b32_e32 v108, v2
	v_mov_b32_e32 v109, v2
	v_mov_b32_e32 v110, v2
	v_mov_b32_e32 v111, v2
	v_mov_b32_e32 v112, v2
	v_mov_b32_e32 v113, v2
	v_mov_b32_e32 v122, v2
	v_mov_b32_e32 v123, v2
	v_mov_b32_e32 v124, v2
	v_mov_b32_e32 v125, v2
	v_mov_b32_e32 v126, v2
	v_mov_b32_e32 v127, v2
	v_mov_b32_e32 v128, v2
	v_mov_b32_e32 v129, v2
	s_barrier
	.p2align	6

.LBB0_1332:
	s_ashr_i32 s17, s16, 31
	s_lshl_b64 s[28:29], s[16:17], 21
	s_add_u32 s36, s30, s28
	s_addc_u32 s37, s31, s29
	s_and_b64 s[28:29], s[26:27], exec
	s_cselect_b32 s17, s37, s25
	s_cselect_b32 s33, s36, s24
	s_ashr_i32 s15, s14, 31
	s_lshl_b64 s[28:29], s[14:15], 21
	s_add_u32 s38, s34, s28
	s_addc_u32 s39, s35, s29
	s_and_b64 s[28:29], s[26:27], exec
	s_cselect_b32 s15, s39, s3
	s_cselect_b32 s58, s38, s2
	s_add_u32 s24, s24, 0x100080
	s_addc_u32 s25, s25, 0
	s_add_u32 s59, s2, 0x100
	v_mov_b32_e32 v10, 0
	s_addc_u32 s60, s3, 0
	s_mov_b32 s61, -2
	v_mov_b32_e32 v11, v10
	v_mov_b32_e32 v12, v10
	v_mov_b32_e32 v13, v10
	v_mov_b32_e32 v14, v10
	v_mov_b32_e32 v15, v10
	v_mov_b32_e32 v16, v10
	v_mov_b32_e32 v17, v10
	v_mov_b32_e32 v26, v10
	v_mov_b32_e32 v27, v10
	v_mov_b32_e32 v28, v10
	v_mov_b32_e32 v29, v10
	v_mov_b32_e32 v30, v10
	v_mov_b32_e32 v31, v10
	v_mov_b32_e32 v32, v10
	v_mov_b32_e32 v33, v10
	v_mov_b32_e32 v42, v10
	v_mov_b32_e32 v43, v10
	v_mov_b32_e32 v44, v10
	v_mov_b32_e32 v45, v10
	v_mov_b32_e32 v46, v10
	v_mov_b32_e32 v47, v10
	v_mov_b32_e32 v48, v10
	v_mov_b32_e32 v49, v10
	v_mov_b32_e32 v58, v10
	v_mov_b32_e32 v59, v10
	v_mov_b32_e32 v60, v10
	v_mov_b32_e32 v61, v10
	v_mov_b32_e32 v62, v10
	v_mov_b32_e32 v63, v10
	v_mov_b32_e32 v64, v10
	v_mov_b32_e32 v65, v10
	v_mov_b32_e32 v2, v10
	v_mov_b32_e32 v3, v10
	v_mov_b32_e32 v4, v10
	v_mov_b32_e32 v5, v10
	v_mov_b32_e32 v6, v10
	v_mov_b32_e32 v7, v10
	v_mov_b32_e32 v8, v10
	v_mov_b32_e32 v9, v10
	v_mov_b32_e32 v18, v10
	v_mov_b32_e32 v19, v10
	v_mov_b32_e32 v20, v10
	v_mov_b32_e32 v21, v10
	v_mov_b32_e32 v22, v10
	v_mov_b32_e32 v23, v10
	v_mov_b32_e32 v24, v10
	v_mov_b32_e32 v25, v10
	v_mov_b32_e32 v34, v10
	v_mov_b32_e32 v35, v10
	v_mov_b32_e32 v36, v10
	v_mov_b32_e32 v37, v10
	v_mov_b32_e32 v38, v10
	v_mov_b32_e32 v39, v10
	v_mov_b32_e32 v40, v10
	v_mov_b32_e32 v41, v10
	v_mov_b32_e32 v50, v10
	v_mov_b32_e32 v51, v10
	v_mov_b32_e32 v52, v10
	v_mov_b32_e32 v53, v10
	v_mov_b32_e32 v54, v10
	v_mov_b32_e32 v55, v10
	v_mov_b32_e32 v56, v10
	v_mov_b32_e32 v57, v10
	v_mov_b32_e32 v74, v10
	v_mov_b32_e32 v75, v10
	v_mov_b32_e32 v76, v10
	v_mov_b32_e32 v77, v10
	v_mov_b32_e32 v78, v10
	v_mov_b32_e32 v79, v10
	v_mov_b32_e32 v80, v10
	v_mov_b32_e32 v81, v10
	v_mov_b32_e32 v90, v10
	v_mov_b32_e32 v91, v10
	v_mov_b32_e32 v92, v10
	v_mov_b32_e32 v93, v10
	v_mov_b32_e32 v94, v10
	v_mov_b32_e32 v95, v10
	v_mov_b32_e32 v96, v10
	v_mov_b32_e32 v97, v10
	v_mov_b32_e32 v106, v10
	v_mov_b32_e32 v107, v10
	v_mov_b32_e32 v108, v10
	v_mov_b32_e32 v109, v10
	v_mov_b32_e32 v110, v10
	v_mov_b32_e32 v111, v10
	v_mov_b32_e32 v112, v10
	v_mov_b32_e32 v113, v10
	v_mov_b32_e32 v122, v10
	v_mov_b32_e32 v123, v10
	v_mov_b32_e32 v124, v10
	v_mov_b32_e32 v125, v10
	v_mov_b32_e32 v126, v10
	v_mov_b32_e32 v127, v10
	v_mov_b32_e32 v128, v10
	v_mov_b32_e32 v129, v10
	v_mov_b32_e32 v66, v10
	v_mov_b32_e32 v67, v10
	v_mov_b32_e32 v68, v10
	v_mov_b32_e32 v69, v10
	v_mov_b32_e32 v70, v10
	v_mov_b32_e32 v71, v10
	v_mov_b32_e32 v72, v10
	v_mov_b32_e32 v73, v10
	v_mov_b32_e32 v82, v10
	v_mov_b32_e32 v83, v10
	v_mov_b32_e32 v84, v10
	v_mov_b32_e32 v85, v10
	v_mov_b32_e32 v86, v10
	v_mov_b32_e32 v87, v10
	v_mov_b32_e32 v88, v10
	v_mov_b32_e32 v89, v10
	v_mov_b32_e32 v98, v10
	v_mov_b32_e32 v99, v10
	v_mov_b32_e32 v100, v10
	v_mov_b32_e32 v101, v10
	v_mov_b32_e32 v102, v10
	v_mov_b32_e32 v103, v10
	v_mov_b32_e32 v104, v10
	v_mov_b32_e32 v105, v10
	v_mov_b32_e32 v114, v10
	v_mov_b32_e32 v115, v10
	v_mov_b32_e32 v116, v10
	v_mov_b32_e32 v117, v10
	v_mov_b32_e32 v118, v10
	v_mov_b32_e32 v119, v10
	v_mov_b32_e32 v120, v10
	v_mov_b32_e32 v121, v10
	.p2align	6

.LBB0_1538:
	s_ashr_i32 s15, s14, 31
	s_lshl_b64 s[22:23], s[14:15], 21
	s_add_u32 s22, s30, s22
	s_addc_u32 s23, s31, s23
	s_and_b64 s[24:25], s[20:21], exec
	s_cselect_b32 s15, s23, s27
	s_cselect_b32 s33, s22, s26
	s_ashr_i32 s13, s12, 31
	s_lshl_b64 s[24:25], s[12:13], 21
	s_add_u32 s24, s34, s24
	s_addc_u32 s25, s35, s25
	s_and_b64 s[28:29], s[20:21], exec
	s_cselect_b32 s13, s25, s3
	s_cselect_b32 s51, s24, s2
	s_add_u32 s26, s26, 0x100080
	s_addc_u32 s27, s27, 0
	s_add_u32 s52, s2, 0x100
	v_mov_b32_e32 v10, 0
	s_addc_u32 s53, s3, 0
	s_mov_b32 s54, -2
	v_mov_b32_e32 v11, v10
	v_mov_b32_e32 v12, v10
	v_mov_b32_e32 v13, v10
	v_mov_b32_e32 v14, v10
	v_mov_b32_e32 v15, v10
	v_mov_b32_e32 v16, v10
	v_mov_b32_e32 v17, v10
	v_mov_b32_e32 v26, v10
	v_mov_b32_e32 v27, v10
	v_mov_b32_e32 v28, v10
	v_mov_b32_e32 v29, v10
	v_mov_b32_e32 v30, v10
	v_mov_b32_e32 v31, v10
	v_mov_b32_e32 v32, v10
	v_mov_b32_e32 v33, v10
	v_mov_b32_e32 v42, v10
	v_mov_b32_e32 v43, v10
	v_mov_b32_e32 v44, v10
	v_mov_b32_e32 v45, v10
	v_mov_b32_e32 v46, v10
	v_mov_b32_e32 v47, v10
	v_mov_b32_e32 v48, v10
	v_mov_b32_e32 v49, v10
	v_mov_b32_e32 v58, v10
	v_mov_b32_e32 v59, v10
	v_mov_b32_e32 v60, v10
	v_mov_b32_e32 v61, v10
	v_mov_b32_e32 v62, v10
	v_mov_b32_e32 v63, v10
	v_mov_b32_e32 v64, v10
	v_mov_b32_e32 v65, v10
	v_mov_b32_e32 v2, v10
	v_mov_b32_e32 v3, v10
	v_mov_b32_e32 v4, v10
	v_mov_b32_e32 v5, v10
	v_mov_b32_e32 v6, v10
	v_mov_b32_e32 v7, v10
	v_mov_b32_e32 v8, v10
	v_mov_b32_e32 v9, v10
	v_mov_b32_e32 v18, v10
	v_mov_b32_e32 v19, v10
	v_mov_b32_e32 v20, v10
	v_mov_b32_e32 v21, v10
	v_mov_b32_e32 v22, v10
	v_mov_b32_e32 v23, v10
	v_mov_b32_e32 v24, v10
	v_mov_b32_e32 v25, v10
	v_mov_b32_e32 v34, v10
	v_mov_b32_e32 v35, v10
	v_mov_b32_e32 v36, v10
	v_mov_b32_e32 v37, v10
	v_mov_b32_e32 v38, v10
	v_mov_b32_e32 v39, v10
	v_mov_b32_e32 v40, v10
	v_mov_b32_e32 v41, v10
	v_mov_b32_e32 v50, v10
	v_mov_b32_e32 v51, v10
	v_mov_b32_e32 v52, v10
	v_mov_b32_e32 v53, v10
	v_mov_b32_e32 v54, v10
	v_mov_b32_e32 v55, v10
	v_mov_b32_e32 v56, v10
	v_mov_b32_e32 v57, v10
	v_mov_b32_e32 v74, v10
	v_mov_b32_e32 v75, v10
	v_mov_b32_e32 v76, v10
	v_mov_b32_e32 v77, v10
	v_mov_b32_e32 v78, v10
	v_mov_b32_e32 v79, v10
	v_mov_b32_e32 v80, v10
	v_mov_b32_e32 v81, v10
	v_mov_b32_e32 v90, v10
	v_mov_b32_e32 v91, v10
	v_mov_b32_e32 v92, v10
	v_mov_b32_e32 v93, v10
	v_mov_b32_e32 v94, v10
	v_mov_b32_e32 v95, v10
	v_mov_b32_e32 v96, v10
	v_mov_b32_e32 v97, v10
	v_mov_b32_e32 v106, v10
	v_mov_b32_e32 v107, v10
	v_mov_b32_e32 v108, v10
	v_mov_b32_e32 v109, v10
	v_mov_b32_e32 v110, v10
	v_mov_b32_e32 v111, v10
	v_mov_b32_e32 v112, v10
	v_mov_b32_e32 v113, v10
	v_mov_b32_e32 v122, v10
	v_mov_b32_e32 v123, v10
	v_mov_b32_e32 v124, v10
	v_mov_b32_e32 v125, v10
	v_mov_b32_e32 v126, v10
	v_mov_b32_e32 v127, v10
	v_mov_b32_e32 v128, v10
	v_mov_b32_e32 v129, v10
	v_mov_b32_e32 v66, v10
	v_mov_b32_e32 v67, v10
	v_mov_b32_e32 v68, v10
	v_mov_b32_e32 v69, v10
	v_mov_b32_e32 v70, v10
	v_mov_b32_e32 v71, v10
	v_mov_b32_e32 v72, v10
	v_mov_b32_e32 v73, v10
	v_mov_b32_e32 v82, v10
	v_mov_b32_e32 v83, v10
	v_mov_b32_e32 v84, v10
	v_mov_b32_e32 v85, v10
	v_mov_b32_e32 v86, v10
	v_mov_b32_e32 v87, v10
	v_mov_b32_e32 v88, v10
	v_mov_b32_e32 v89, v10
	v_mov_b32_e32 v98, v10
	v_mov_b32_e32 v99, v10
	v_mov_b32_e32 v100, v10
	v_mov_b32_e32 v101, v10
	v_mov_b32_e32 v102, v10
	v_mov_b32_e32 v103, v10
	v_mov_b32_e32 v104, v10
	v_mov_b32_e32 v105, v10
	v_mov_b32_e32 v114, v10
	v_mov_b32_e32 v115, v10
	v_mov_b32_e32 v116, v10
	v_mov_b32_e32 v117, v10
	v_mov_b32_e32 v118, v10
	v_mov_b32_e32 v119, v10
	v_mov_b32_e32 v120, v10
	v_mov_b32_e32 v121, v10
	.p2align	6

.LBB0_1549:
	v_lshlrev_b32_e32 v9, 2, v155
	v_lshl_or_b32 v8, v155, 6, v151
	s_lshl_b32 s1, s15, 12
	v_and_b32_e32 v9, 32, v9
	v_lshl_or_b32 v68, s15, 5, v155
	v_bitop3_b32 v8, v8, s1, v9 bitop3:0xde
	s_lshl_b32 s1, s14, 5
	s_mov_b64 s[14:15], 0x80
	s_add_i32 m0, s3, 0x18000
	v_lshl_add_u64 v[4:5], v[4:5], 0, s[14:15]
	s_and_b32 s1, s1, 0x60
	s_waitcnt vmcnt(1)
	s_barrier
	global_load_lds_dwordx4 v[4:5], off
	s_add_i32 m0, s3, 0x1a000
	s_add_i32 s24, s3, 0x8000
	v_lshl_add_u64 v[4:5], v[6:7], 0, s[14:15]
	s_add_u32 s26, s8, 0x100080
	global_load_lds_dwordx4 v[4:5], off
	v_lshl_add_u64 v[2:3], v[2:3], 0, s[14:15]
	s_mov_b32 m0, s24
	s_addc_u32 s27, s9, 0
	global_load_lds_dwordx4 v[2:3], off
	s_add_i32 m0, s3, 0x1c000
	v_lshl_add_u64 v[2:3], s[26:27], 0, v[132:133]
	global_load_lds_dwordx4 v[2:3], off
	v_lshl_add_u64 v[2:3], s[26:27], 0, v[134:135]
	s_add_i32 m0, s3, 0x1e000
	s_add_u32 s16, s84, s16
	global_load_lds_dwordx4 v[2:3], off
	s_addc_u32 s17, s85, s17
	s_add_u32 s16, s16, 0x2f000100
	s_addc_u32 s17, s17, 0
	s_add_u32 s18, s84, s18
	s_addc_u32 s19, s85, s19
	v_lshlrev_b32_e32 v2, 10, v0
	s_add_u32 s25, s18, 0xfc00100
	v_lshl_or_b32 v9, s1, 7, v150
	s_waitcnt vmcnt(5)
	v_and_b32_e32 v2, 0x60000, v2
	v_lshlrev_b32_e32 v3, 13, v186
	s_addc_u32 s26, s19, 0
	s_add_i32 s29, 0, 0x10000
	s_add_i32 s31, 0, 0x14000
	s_add_i32 s34, 0, 0x18000
	s_add_i32 s36, 0, 0x1c000
	v_or3_b32 v2, v149, v2, v3
	v_add_u32_e32 v69, s29, v9
	v_add_u32_e32 v70, s31, v9
	s_add_i32 s29, s29, s20
	s_add_i32 s31, s31, s20
	v_add_u32_e32 v72, s34, v9
	v_add_u32_e32 v73, s36, v9
	s_add_i32 s34, s34, s20
	s_add_i32 s36, s36, s20
	v_add_u32_e32 v66, v2, v185
	v_mov_b32_e32 v67, v133
	s_mov_b32 s27, -2
	v_add_u32_e32 v71, 0, v8
	s_mov_b64 s[18:19], 0x7ff80
	s_add_i32 s28, s3, 0xc000
	s_add_i32 s30, s29, 0x2000
	s_add_i32 s33, s31, 0x2000
	s_add_i32 s35, s34, 0x2000
	s_add_i32 s37, s36, 0x2000
	v_mov_b32_e32 v10, v133
	v_mov_b32_e32 v11, v133
	v_mov_b32_e32 v12, v133
	v_mov_b32_e32 v13, v133
	v_mov_b32_e32 v14, v133
	v_mov_b32_e32 v15, v133
	v_mov_b32_e32 v16, v133
	v_mov_b32_e32 v17, v133
	v_mov_b32_e32 v26, v133
	v_mov_b32_e32 v27, v133
	v_mov_b32_e32 v28, v133
	v_mov_b32_e32 v29, v133
	v_mov_b32_e32 v30, v133
	v_mov_b32_e32 v31, v133
	v_mov_b32_e32 v32, v133
	v_mov_b32_e32 v33, v133
	v_mov_b32_e32 v2, v133
	v_mov_b32_e32 v3, v133
	v_mov_b32_e32 v4, v133
	v_mov_b32_e32 v5, v133
	v_mov_b32_e32 v6, v133
	v_mov_b32_e32 v7, v133
	v_mov_b32_e32 v8, v133
	v_mov_b32_e32 v9, v133
	v_mov_b32_e32 v18, v133
	v_mov_b32_e32 v19, v133
	v_mov_b32_e32 v20, v133
	v_mov_b32_e32 v21, v133
	v_mov_b32_e32 v22, v133
	v_mov_b32_e32 v23, v133
	v_mov_b32_e32 v24, v133
	v_mov_b32_e32 v25, v133
	v_mov_b32_e32 v42, v133
	v_mov_b32_e32 v43, v133
	v_mov_b32_e32 v44, v133
	v_mov_b32_e32 v45, v133
	v_mov_b32_e32 v46, v133
	v_mov_b32_e32 v47, v133
	v_mov_b32_e32 v48, v133
	v_mov_b32_e32 v49, v133
	v_mov_b32_e32 v58, v133
	v_mov_b32_e32 v59, v133
	v_mov_b32_e32 v60, v133
	v_mov_b32_e32 v61, v133
	v_mov_b32_e32 v62, v133
	v_mov_b32_e32 v63, v133
	v_mov_b32_e32 v64, v133
	v_mov_b32_e32 v65, v133
	v_mov_b32_e32 v34, v133
	v_mov_b32_e32 v35, v133
	v_mov_b32_e32 v36, v133
	v_mov_b32_e32 v37, v133
	v_mov_b32_e32 v38, v133
	v_mov_b32_e32 v39, v133
	v_mov_b32_e32 v40, v133
	v_mov_b32_e32 v41, v133
	v_mov_b32_e32 v50, v133
	v_mov_b32_e32 v51, v133
	v_mov_b32_e32 v52, v133
	v_mov_b32_e32 v53, v133
	v_mov_b32_e32 v54, v133
	v_mov_b32_e32 v55, v133
	v_mov_b32_e32 v56, v133
	v_mov_b32_e32 v57, v133
	s_barrier
	.p2align	6

.LBB0_1729:
	s_add_u32 s2, s2, 0x2b0080
	s_addc_u32 s3, s3, 0
	s_add_u32 s56, s24, 0x100
	v_mov_b32_e32 v2, 0
	s_addc_u32 s57, s25, 0
	s_mov_b32 s58, -2
	v_mov_b32_e32 v3, v2
	v_mov_b32_e32 v4, v2
	v_mov_b32_e32 v5, v2
	v_mov_b32_e32 v6, v2
	v_mov_b32_e32 v7, v2
	v_mov_b32_e32 v8, v2
	v_mov_b32_e32 v9, v2
	v_mov_b32_e32 v18, v2
	v_mov_b32_e32 v19, v2
	v_mov_b32_e32 v20, v2
	v_mov_b32_e32 v21, v2
	v_mov_b32_e32 v22, v2
	v_mov_b32_e32 v23, v2
	v_mov_b32_e32 v24, v2
	v_mov_b32_e32 v25, v2
	v_mov_b32_e32 v34, v2
	v_mov_b32_e32 v35, v2
	v_mov_b32_e32 v36, v2
	v_mov_b32_e32 v37, v2
	v_mov_b32_e32 v38, v2
	v_mov_b32_e32 v39, v2
	v_mov_b32_e32 v40, v2
	v_mov_b32_e32 v41, v2
	v_mov_b32_e32 v50, v2
	v_mov_b32_e32 v51, v2
	v_mov_b32_e32 v52, v2
	v_mov_b32_e32 v53, v2
	v_mov_b32_e32 v54, v2
	v_mov_b32_e32 v55, v2
	v_mov_b32_e32 v56, v2
	v_mov_b32_e32 v57, v2
	v_mov_b32_e32 v10, v2
	v_mov_b32_e32 v11, v2
	v_mov_b32_e32 v12, v2
	v_mov_b32_e32 v13, v2
	v_mov_b32_e32 v14, v2
	v_mov_b32_e32 v15, v2
	v_mov_b32_e32 v16, v2
	v_mov_b32_e32 v17, v2
	v_mov_b32_e32 v26, v2
	v_mov_b32_e32 v27, v2
	v_mov_b32_e32 v28, v2
	v_mov_b32_e32 v29, v2
	v_mov_b32_e32 v30, v2
	v_mov_b32_e32 v31, v2
	v_mov_b32_e32 v32, v2
	v_mov_b32_e32 v33, v2
	v_mov_b32_e32 v42, v2
	v_mov_b32_e32 v43, v2
	v_mov_b32_e32 v44, v2
	v_mov_b32_e32 v45, v2
	v_mov_b32_e32 v46, v2
	v_mov_b32_e32 v47, v2
	v_mov_b32_e32 v48, v2
	v_mov_b32_e32 v49, v2
	v_mov_b32_e32 v58, v2
	v_mov_b32_e32 v59, v2
	v_mov_b32_e32 v60, v2
	v_mov_b32_e32 v61, v2
	v_mov_b32_e32 v62, v2
	v_mov_b32_e32 v63, v2
	v_mov_b32_e32 v64, v2
	v_mov_b32_e32 v65, v2
	v_mov_b32_e32 v66, v2
	v_mov_b32_e32 v67, v2
	v_mov_b32_e32 v68, v2
	v_mov_b32_e32 v69, v2
	v_mov_b32_e32 v70, v2
	v_mov_b32_e32 v71, v2
	v_mov_b32_e32 v72, v2
	v_mov_b32_e32 v73, v2
	v_mov_b32_e32 v82, v2
	v_mov_b32_e32 v83, v2
	v_mov_b32_e32 v84, v2
	v_mov_b32_e32 v85, v2
	v_mov_b32_e32 v86, v2
	v_mov_b32_e32 v87, v2
	v_mov_b32_e32 v88, v2
	v_mov_b32_e32 v89, v2
	v_mov_b32_e32 v98, v2
	v_mov_b32_e32 v99, v2
	v_mov_b32_e32 v100, v2
	v_mov_b32_e32 v101, v2
	v_mov_b32_e32 v102, v2
	v_mov_b32_e32 v103, v2
	v_mov_b32_e32 v104, v2
	v_mov_b32_e32 v105, v2
	v_mov_b32_e32 v110, v2
	v_mov_b32_e32 v111, v2
	v_mov_b32_e32 v112, v2
	v_mov_b32_e32 v113, v2
	v_mov_b32_e32 v118, v2
	v_mov_b32_e32 v119, v2
	v_mov_b32_e32 v120, v2
	v_mov_b32_e32 v121, v2
	v_mov_b32_e32 v74, v2
	v_mov_b32_e32 v75, v2
	v_mov_b32_e32 v76, v2
	v_mov_b32_e32 v77, v2
	v_mov_b32_e32 v78, v2
	v_mov_b32_e32 v79, v2
	v_mov_b32_e32 v80, v2
	v_mov_b32_e32 v81, v2
	v_mov_b32_e32 v90, v2
	v_mov_b32_e32 v91, v2
	v_mov_b32_e32 v92, v2
	v_mov_b32_e32 v93, v2
	v_mov_b32_e32 v94, v2
	v_mov_b32_e32 v95, v2
	v_mov_b32_e32 v96, v2
	v_mov_b32_e32 v97, v2
	v_mov_b32_e32 v106, v2
	v_mov_b32_e32 v107, v2
	v_mov_b32_e32 v108, v2
	v_mov_b32_e32 v109, v2
	v_mov_b32_e32 v114, v2
	v_mov_b32_e32 v115, v2
	v_mov_b32_e32 v116, v2
	v_mov_b32_e32 v117, v2
	v_mov_b32_e32 v122, v2
	v_mov_b32_e32 v123, v2
	v_mov_b32_e32 v124, v2
	v_mov_b32_e32 v125, v2
	v_mov_b32_e32 v126, v2
	v_mov_b32_e32 v127, v2
	v_mov_b32_e32 v128, v2
	v_mov_b32_e32 v129, v2
	.p2align	6

.LBB0_1739:
	s_lshr_b32 s24, s87, 3
	s_cmp_eq_u32 s4, 3
	s_cselect_b32 s16, 44, 46
	s_and_b64 s[12:13], s[12:13], exec
	v_lshlrev_b32_e32 v11, 2, v155
	s_cselect_b32 s26, 36, s16
	v_lshl_or_b32 v10, v155, 6, v184
	v_and_b32_e32 v11, 32, v11
	s_lshl_b32 s12, s15, 5
	s_lshl_b32 s13, s14, 13
	s_and_b32 s20, s12, 0x60
	v_bitop3_b32 v10, v10, s13, v11 bitop3:0xde
	s_mov_b64 s[12:13], 0x80
	s_add_i32 m0, s21, 0x18000
	v_lshl_add_u64 v[2:3], v[2:3], 0, s[12:13]
	s_waitcnt vmcnt(2)
	s_barrier
	global_load_lds_dwordx4 v[2:3], off
	v_lshl_add_u64 v[2:3], v[4:5], 0, s[12:13]
	s_add_i32 m0, s21, 0x1a000
	s_add_i32 s27, s21, 0x8000
	s_add_i32 s28, s21, 0xa000
	v_lshl_or_b32 v132, s14, 6, v155
	global_load_lds_dwordx4 v[2:3], off
	v_lshl_add_u64 v[2:3], v[8:9], 0, s[12:13]
	s_mov_b32 m0, s27
	s_add_u32 s14, s2, 0x2b0080
	global_load_lds_dwordx4 v[2:3], off
	v_lshl_add_u64 v[2:3], v[6:7], 0, s[12:13]
	s_mov_b32 m0, s28
	s_addc_u32 s15, s3, 0
	global_load_lds_dwordx4 v[2:3], off
	s_add_i32 m0, s21, 0x1c000
	v_lshl_add_u64 v[2:3], s[14:15], 0, v[158:159]
	global_load_lds_dwordx4 v[2:3], off
	v_lshl_add_u64 v[2:3], s[14:15], 0, v[160:161]
	s_add_i32 m0, s21, 0x1e000
	v_lshl_or_b32 v12, s20, 7, v157
	global_load_lds_dwordx4 v[2:3], off
	s_waitcnt vmcnt(6)
	s_add_i32 s33, 0, 0x10000
	s_add_i32 s35, 0, 0x14000
	s_add_i32 s37, 0, 0x18000
	s_add_i32 s39, 0, 0x1c000
	v_mov_b32_e32 v2, 0
	v_add_u32_e32 v130, s33, v12
	v_add_u32_e32 v131, s35, v12
	s_add_i32 s33, s33, s10
	s_add_i32 s35, s35, s10
	v_add_u32_e32 v134, s37, v12
	v_add_u32_e32 v135, s39, v12
	s_add_i32 s37, s37, s10
	s_add_i32 s39, s39, s10
	s_add_i32 s29, s26, -2
	v_add_u32_e32 v133, 0, v10
	s_add_i32 s30, s21, 0xc000
	s_add_i32 s31, s21, 0xe000
	s_add_i32 s34, s33, 0x2000
	s_add_i32 s36, s35, 0x2000
	s_add_i32 s38, s37, 0x2000
	s_add_i32 s40, s39, 0x2000
	s_mov_b32 s14, 0
	v_mov_b32_e32 v3, v2
	v_mov_b32_e32 v4, v2
	v_mov_b32_e32 v5, v2
	v_mov_b32_e32 v6, v2
	v_mov_b32_e32 v7, v2
	v_mov_b32_e32 v8, v2
	v_mov_b32_e32 v9, v2
	v_mov_b32_e32 v18, v2
	v_mov_b32_e32 v19, v2
	v_mov_b32_e32 v20, v2
	v_mov_b32_e32 v21, v2
	v_mov_b32_e32 v22, v2
	v_mov_b32_e32 v23, v2
	v_mov_b32_e32 v24, v2
	v_mov_b32_e32 v25, v2
	v_mov_b32_e32 v34, v2
	v_mov_b32_e32 v35, v2
	v_mov_b32_e32 v36, v2
	v_mov_b32_e32 v37, v2
	v_mov_b32_e32 v38, v2
	v_mov_b32_e32 v39, v2
	v_mov_b32_e32 v40, v2
	v_mov_b32_e32 v41, v2
	v_mov_b32_e32 v50, v2
	v_mov_b32_e32 v51, v2
	v_mov_b32_e32 v52, v2
	v_mov_b32_e32 v53, v2
	v_mov_b32_e32 v54, v2
	v_mov_b32_e32 v55, v2
	v_mov_b32_e32 v56, v2
	v_mov_b32_e32 v57, v2
	v_mov_b32_e32 v10, v2
	v_mov_b32_e32 v11, v2
	v_mov_b32_e32 v12, v2
	v_mov_b32_e32 v13, v2
	v_mov_b32_e32 v14, v2
	v_mov_b32_e32 v15, v2
	v_mov_b32_e32 v16, v2
	v_mov_b32_e32 v17, v2
	v_mov_b32_e32 v26, v2
	v_mov_b32_e32 v27, v2
	v_mov_b32_e32 v28, v2
	v_mov_b32_e32 v29, v2
	v_mov_b32_e32 v30, v2
	v_mov_b32_e32 v31, v2
	v_mov_b32_e32 v32, v2
	v_mov_b32_e32 v33, v2
	v_mov_b32_e32 v42, v2
	v_mov_b32_e32 v43, v2
	v_mov_b32_e32 v44, v2
	v_mov_b32_e32 v45, v2
	v_mov_b32_e32 v46, v2
	v_mov_b32_e32 v47, v2
	v_mov_b32_e32 v48, v2
	v_mov_b32_e32 v49, v2
	v_mov_b32_e32 v58, v2
	v_mov_b32_e32 v59, v2
	v_mov_b32_e32 v60, v2
	v_mov_b32_e32 v61, v2
	v_mov_b32_e32 v62, v2
	v_mov_b32_e32 v63, v2
	v_mov_b32_e32 v64, v2
	v_mov_b32_e32 v65, v2
	v_mov_b32_e32 v66, v2
	v_mov_b32_e32 v67, v2
	v_mov_b32_e32 v68, v2
	v_mov_b32_e32 v69, v2
	v_mov_b32_e32 v70, v2
	v_mov_b32_e32 v71, v2
	v_mov_b32_e32 v72, v2
	v_mov_b32_e32 v73, v2
	v_mov_b32_e32 v82, v2
	v_mov_b32_e32 v83, v2
	v_mov_b32_e32 v84, v2
	v_mov_b32_e32 v85, v2
	v_mov_b32_e32 v86, v2
	v_mov_b32_e32 v87, v2
	v_mov_b32_e32 v88, v2
	v_mov_b32_e32 v89, v2
	v_mov_b32_e32 v98, v2
	v_mov_b32_e32 v99, v2
	v_mov_b32_e32 v100, v2
	v_mov_b32_e32 v101, v2
	v_mov_b32_e32 v102, v2
	v_mov_b32_e32 v103, v2
	v_mov_b32_e32 v104, v2
	v_mov_b32_e32 v105, v2
	v_mov_b32_e32 v114, v2
	v_mov_b32_e32 v115, v2
	v_mov_b32_e32 v116, v2
	v_mov_b32_e32 v117, v2
	v_mov_b32_e32 v118, v2
	v_mov_b32_e32 v119, v2
	v_mov_b32_e32 v120, v2
	v_mov_b32_e32 v121, v2
	v_mov_b32_e32 v74, v2
	v_mov_b32_e32 v75, v2
	v_mov_b32_e32 v76, v2
	v_mov_b32_e32 v77, v2
	v_mov_b32_e32 v78, v2
	v_mov_b32_e32 v79, v2
	v_mov_b32_e32 v80, v2
	v_mov_b32_e32 v81, v2
	v_mov_b32_e32 v90, v2
	v_mov_b32_e32 v91, v2
	v_mov_b32_e32 v92, v2
	v_mov_b32_e32 v93, v2
	v_mov_b32_e32 v94, v2
	v_mov_b32_e32 v95, v2
	v_mov_b32_e32 v96, v2
	v_mov_b32_e32 v97, v2
	v_mov_b32_e32 v106, v2
	v_mov_b32_e32 v107, v2
	v_mov_b32_e32 v108, v2
	v_mov_b32_e32 v109, v2
	v_mov_b32_e32 v110, v2
	v_mov_b32_e32 v111, v2
	v_mov_b32_e32 v112, v2
	v_mov_b32_e32 v113, v2
	v_mov_b32_e32 v122, v2
	v_mov_b32_e32 v123, v2
	v_mov_b32_e32 v124, v2
	v_mov_b32_e32 v125, v2
	v_mov_b32_e32 v126, v2
	v_mov_b32_e32 v127, v2
	v_mov_b32_e32 v128, v2
	v_mov_b32_e32 v129, v2
	s_barrier
	.p2align	6
